# scan loader: per-head parameter vectors kept in registers (reloaded only when the job head changes) instead of 8 loads + waits per scan_finish call
# speedup vs baseline: 1.0131x; 1.0131x over previous
; #define KP(f) ((decltype(Params::f))karg_ptr<(int)offsetof(Params, f)>())
; __device__ void phase_scan(int l, unsigned char* lds) {
;     int tid_ = threadIdx.x; asm volatile("" : "+v"(tid_));
;     const int tid = tid_, wid = tid >> 6, lane = tid & 63, G = gridDim.x;
;     const bool loader = wid >= 4;
;     if (!loader) __builtin_amdgcn_s_setprio(3);
;     ScanPtrs Q;
;     Q.z = KP(z); Q.sw = KP(xb) + (size_t)T_ALL * 512; Q.sa = KP(sc_a); Q.st_shift = KP(state_shift) + (size_t)l * NSB * DSH; Q.mu = KP(mu_shift) + (size_t)l * DSH;
;     Q.k_k = KP(k_k) + (size_t)l * 512; Q.k_a = KP(k_a) + (size_t)l * 512; Q.r_k = KP(r_k) + (size_t)l * 512; Q.decay0 = KP(decay0) + (size_t)l * 512; Q.a0 = KP(a0) + (size_t)l * 512; Q.rk = KP(rk);
;     bf16_t* ybuf = KP(xb);
;     const float* st_wkv = KP(state_wkv); float* out = KP(out);
;     int J = (G % 8 == 0) ? (int)(blockIdx.x % 8) * (G / 8) + (int)(blockIdx.x / 8) : (int)blockIdx.x, ci = 0, it = 0;
;     int Ji = J, cis = 0;
;     int Jg = J, cg_ = 0;
;     LStage L, L2;
;     f32x2 s01 = (f32x2){0.f, 0.f}, s23 = s01;
;     f32x4 s_pref = (f32x4){0.f, 0.f, 0.f, 0.f};
;     if (!loader && J >= 256 && J < NJOBS) { const Job j0 = job_decode(J, 0); s_pref = *(const f32x4*)(st_wkv + (((((size_t)l * NSB + j0.seq) * 8 + j0.h) * 64 + j0.rs * 16 + (wid * 4 + (lane >> 4))) * 64 + (lane & 15) * 4)); }
.LBB0_401:
	s_or_b64 exec, exec, s[8:9]
	s_mov_b32 s6, s46
	s_mov_b32 s7, s2
	v_mov_b32_e32 v53, v166
	s_waitcnt lgkmcnt(0)
	s_barrier
	s_nop 0
	v_ashrrev_i32_e32 v52, 6, v53
	s_mov_b32 s98, -1
	v_cmp_lt_i32_e64 s[10:11], 3, v52
	v_cmp_gt_i32_e64 s[12:13], 4, v52
	s_and_saveexec_b64 s[8:9], s[12:13]
	s_setprio 3
	s_or_b64 exec, exec, s[8:9]
	s_load_dwordx2 s[24:25], s[0:1], 0x130
	s_waitcnt lgkmcnt(0)
	s_load_dwordx2 s[14:15], s[0:1], 0x120
	s_waitcnt lgkmcnt(0)
	s_load_dwordx2 s[26:27], s[0:1], 0x140
	s_waitcnt lgkmcnt(0)
	s_load_dwordx2 s[28:29], s[0:1], 16
	s_waitcnt lgkmcnt(0)
	s_load_dwordx2 s[30:31], s[0:1], 56
	s_waitcnt lgkmcnt(0)
	s_load_dwordx2 s[34:35], s[0:1], 0x68
	s_waitcnt lgkmcnt(0)
	s_load_dwordx2 s[36:37], s[0:1], 0x70
	s_waitcnt lgkmcnt(0)
	s_load_dwordx2 s[38:39], s[0:1], 0x78
	s_waitcnt lgkmcnt(0)
	s_load_dwordx2 s[40:41], s[0:1], 64
	s_waitcnt lgkmcnt(0)
	s_load_dwordx2 s[56:57], s[0:1], 0x50
	s_waitcnt lgkmcnt(0)
	s_load_dwordx2 s[58:59], s[0:1], 0x150
	s_waitcnt lgkmcnt(0)
	s_load_dwordx2 s[60:61], s[0:1], 0x120
	s_waitcnt lgkmcnt(0)
	s_load_dwordx2 s[22:23], s[0:1], 32
	s_waitcnt lgkmcnt(0)
	s_load_dwordx2 s[62:63], s[0:1], 0xd8
	s_waitcnt lgkmcnt(0)
	v_cndmask_b32_e64 v0, 0, 1, s[54:55]
	v_cmp_ne_u32_e64 s[6:7], 1, v0
	s_andn2_b64 vcc, exec, s[54:55]
	s_mov_b32 s51, s2
	v_writelane_b32 v230, s6, 6
	s_nop 1
	v_writelane_b32 v230, s7, 7
	s_cbranch_vccnz .LBB0_405
	s_and_b32 s6, s2, 7
	s_ashr_i32 s7, s46, 3
	s_mul_i32 s6, s7, s6
	s_lshr_b32 s7, s2, 3
	s_add_i32 s51, s6, s7

; __device__ __forceinline__ float sigmoidf_(float x) { return 1.0f / (1.0f + __expf(-x)); }
; __device__ __forceinline__ f32x4 cv_bf4(const u32x2 w) { return (f32x4){bflo(w.x), bfhi(w.x), bflo(w.y), bfhi(w.y)}; }
; __device__ __forceinline__ void scan_finish(const ScanPtrs& Q, int J, int ci, unsigned char* buf, int ltid, const LStage& L, int toff) {
;     ...
;         const float* mu = Q.mu + gc;
;         r = r + (rp - r) * *(const f32x4*)mu; k0 = k0 + (kp - k0) * *(const f32x4*)(mu + 512); v = v + (vp - v) * *(const f32x4*)(mu + 1024);
;         const f32x4 kk = k0 * *(const f32x4*)(Q.k_k + gc);
;         const float ss = allsum16((kk[0] * kk[0] + kk[1] * kk[1]) + (kk[2] * kk[2] + kk[3] * kk[3]));
;         const float inv = 1.0f / fmaxf(sqrtf(ss), 1e-12f);
;         const f32x4 kkn = kk * inv;
;         const f32x4 dw = cv_bf4(L.sw) + *(const f32x4*)(Q.decay0 + gc);
;         const f32x4 da = cv_bf4(L.sa) + *(const f32x4*)(Q.a0 + gc);
;         f32x4 dec, ain;
; #pragma unroll
;         for (int j = 0; j < 4; ++j) { dec[j] = __expf(-0.60653066f * sigmoidf_(dw[j])); ain[j] = sigmoidf_(da[j]); }
;         const f32x4 ka = *(const f32x4*)(Q.k_a + gc);
;         const f32x4 kf = k0 * (1.0f + (ain - 1.0f) * ka);
;         const f32x4 rkw = *(const f32x4*)(Q.r_k + gc);
;         const f32x4 pr = r * kf * rkw;
;         const float rk = allsum16((pr[0] + pr[1]) + (pr[2] + pr[3]));
;         unsigned char* tb = buf + tt * SC_TOKB + c * 4;
;         *(f32x4*)(tb) = -kkn; *(f32x4*)(tb + 256) = dec; *(f32x4*)(tb + 512) = kkn * ain; *(f32x4*)(tb + 768) = kf; *(f32x4*)(tb + 1024) = r;
;         if ((c >> 4) == jb.rs) *(f32x4*)(buf + tt * SC_TOKB + 1280 + (c & 15) * 4) = v;
.LBB0_488:
	s_or_b64 exec, exec, s[18:19]
	v_lshl_or_b32 v18, v91, 8, v100
	v_readfirstlane_b32 s99, v91
	s_nop 3
	s_cmp_eq_u32 s99, s98
	s_cbranch_scc1 .Lprm_ok_0
	s_mov_b32 s98, s99
	s_lshl_b32 s99, s99, 8
	s_mov_b64 s[100:101], exec
	s_mov_b64 exec, -1
	v_or_b32_e32 v229, s99, v100
	global_load_dwordx4 v[186:189], v229, s[30:31] offset:2048
	global_load_dwordx4 v[190:193], v229, s[40:41]
	global_load_dwordx4 v[194:197], v229, s[56:57]
	global_load_dwordx4 v[198:201], v229, s[34:35]
	global_load_dwordx4 v[202:205], v229, s[30:31]
	global_load_dwordx4 v[206:209], v229, s[36:37]
	global_load_dwordx4 v[210:213], v229, s[38:39]
	v_add_u32_e32 v228, 0x1000, v229
	global_load_dwordx4 v[214:217], v228, s[30:31]
	s_waitcnt vmcnt(0)
	s_mov_b64 exec, s[100:101]
.Lprm_ok_0:
	s_waitcnt vmcnt(3)
	v_lshlrev_b32_e32 v132, 16, v70
	v_and_b32_e32 v133, 0xffff0000, v70
	v_lshlrev_b32_e32 v134, 16, v71
	v_and_b32_e32 v135, 0xffff0000, v71
	v_sub_f32_e32 v137, v51, v133
	v_sub_f32_e32 v136, v50, v132
	v_sub_f32_e32 v139, v53, v135
	v_sub_f32_e32 v138, v52, v134
	s_waitcnt vmcnt(1)
	v_lshlrev_b32_e32 v123, 16, v82
	v_and_b32_e32 v140, 0xffff0000, v82
	v_lshlrev_b32_e32 v141, 16, v83
	s_waitcnt vmcnt(0)
	v_lshlrev_b32_e32 v143, 16, v84
	v_and_b32_e32 v142, 0xffff0000, v83
	v_and_b32_e32 v146, 0xffff0000, v84
	v_lshlrev_b32_e32 v147, 16, v85
	v_and_b32_e32 v148, 0xffff0000, v85
	v_lshlrev_b32_e32 v20, 16, v62
	v_and_b32_e32 v21, 0xffff0000, v62
	v_lshlrev_b32_e32 v92, 16, v63
	v_and_b32_e32 v93, 0xffff0000, v63
	v_sub_f32_e32 v47, v47, v21
	v_sub_f32_e32 v46, v46, v20
	v_sub_f32_e32 v49, v49, v93
	v_sub_f32_e32 v48, v48, v92
	s_waitcnt vmcnt(0)
	v_pk_fma_f32 v[44:45], v[138:139], v[188:189], v[134:135]
	v_pk_fma_f32 v[42:43], v[136:137], v[186:187], v[132:133]
	s_waitcnt vmcnt(0)
	v_add_f32_e32 v38, v190, v123
	v_add_f32_e32 v39, v191, v140
	s_waitcnt vmcnt(0)
	v_pk_mul_f32 v[126:127], v[44:45], v[200:201]
	v_pk_mul_f32 v[124:125], v[42:43], v[198:199]
	v_mul_f32_e32 v123, 0xbfb8aa3b, v38
	v_mul_f32_e32 v134, 0xbfb8aa3b, v39
	v_pk_mul_f32 v[38:39], v[126:127], v[126:127]
	v_pk_mul_f32 v[132:133], v[124:125], v[124:125]
	v_exp_f32_e32 v123, v123
	v_exp_f32_e32 v136, v134
	v_pk_mov_b32 v[134:135], v[132:133], v[38:39] op_sel:[1,0]
	v_mov_b32_e32 v133, v39
	v_pk_add_f32 v[38:39], v[134:135], v[132:133]
	v_add_f32_e32 v40, v192, v141
	v_add_f32_e32 v38, v38, v39
	v_add_f32_e32 v39, 1.0, v123
	v_add_f32_e32 v123, 1.0, v136
	v_add_f32_dpp v38, v38, v38 quad_perm:[1,0,3,2] row_mask:0xf bank_mask:0xf bound_ctrl:1
	v_div_scale_f32 v132, s[8:9], v39, v39, 1.0
	s_nop 0
	v_add_f32_dpp v38, v38, v38 quad_perm:[2,3,0,1] row_mask:0xf bank_mask:0xf bound_ctrl:1
	v_div_scale_f32 v134, s[8:9], v123, v123, 1.0
	s_nop 0
	v_add_f32_dpp v38, v38, v38 row_half_mirror row_mask:0xf bank_mask:0xf bound_ctrl:1
	v_rcp_f32_e32 v136, v132
	v_rcp_f32_e32 v137, v134
	v_add_f32_dpp v38, v38, v38 row_mirror row_mask:0xf bank_mask:0xf bound_ctrl:1
	v_mul_f32_e32 v138, 0x4f800000, v38
	v_cmp_gt_f32_e32 vcc, s78, v38
	v_fma_f32 v139, -v132, v136, 1.0
	v_div_scale_f32 v133, s[18:19], 1.0, v39, 1.0
	v_cndmask_b32_e32 v38, v38, v138, vcc
	v_sqrt_f32_e32 v138, v38
	v_fma_f32 v140, -v134, v137, 1.0
	v_fmac_f32_e32 v136, v139, v136
	v_div_scale_f32 v135, s[20:21], 1.0, v123, 1.0
	v_fmac_f32_e32 v137, v140, v137
	v_mul_f32_e32 v139, v133, v136
	v_mul_f32_e32 v140, v135, v137
	v_fma_f32 v141, -v132, v139, v133
	v_add_u32_e32 v149, -1, v138
	v_add_f32_e32 v34, v194, v143
	v_fma_f32 v143, -v134, v140, v135
	v_add_u32_e32 v150, 1, v138
	v_fmac_f32_e32 v139, v141, v136
	v_fma_f32 v141, -v149, v138, v38
	v_fmac_f32_e32 v140, v143, v137
	v_fma_f32 v143, -v150, v138, v38
	v_cmp_ge_f32_e64 s[22:23], 0, v141
	v_fma_f32 v133, -v132, v139, v133
	v_fma_f32 v134, -v134, v140, v135
	v_cndmask_b32_e64 v132, v138, v149, s[22:23]
	v_cmp_lt_f32_e64 s[22:23], 0, v143
	v_mul_f32_e32 v40, 0xbfb8aa3b, v40
	v_exp_f32_e32 v40, v40
	v_cndmask_b32_e64 v132, v132, v150, s[22:23]
	v_mul_f32_e32 v138, 0x37800000, v132
	v_cndmask_b32_e32 v132, v132, v138, vcc
	v_cmp_class_f32_e32 vcc, v38, v118
	v_add_f32_e32 v40, 1.0, v40
	v_add_f32_e32 v41, v193, v142
	v_cndmask_b32_e32 v38, v132, v38, vcc
	v_max_f32_e32 v38, 0x2b8cbccc, v38
	v_div_scale_f32 v132, s[8:9], v38, v38, -1.0
	v_rcp_f32_e32 v138, v132
	v_div_scale_f32 v135, vcc, -1.0, v38, -1.0
	v_mul_f32_e32 v41, 0xbfb8aa3b, v41
	v_fma_f32 v141, -v132, v138, 1.0
	v_fmac_f32_e32 v138, v141, v138
	v_mul_f32_e32 v141, v135, v138
	v_fma_f32 v143, -v132, v141, v135
	v_fmac_f32_e32 v141, v143, v138
	v_fma_f32 v132, -v132, v141, v135
	v_div_fmas_f32 v132, v132, v138, v141
	s_mov_b64 vcc, s[18:19]
	v_div_fixup_f32 v132, v132, v38, -1.0
	v_div_fmas_f32 v38, v133, v136, v139
	s_mov_b64 vcc, s[20:21]
	v_div_fixup_f32 v38, v38, v39, 1.0
	v_div_fmas_f32 v39, v134, v137, v140
	v_div_fixup_f32 v39, v39, v123, 1.0
	v_div_scale_f32 v123, s[8:9], v40, v40, 1.0
	v_rcp_f32_e32 v133, v123
	v_exp_f32_e32 v41, v41
	v_add_f32_e32 v35, v195, v146
	v_mul_f32_e32 v34, 0xbfb8aa3b, v34
	v_fma_f32 v134, -v123, v133, 1.0
	v_fmac_f32_e32 v133, v134, v133
	v_div_scale_f32 v134, vcc, 1.0, v40, 1.0
	v_mul_f32_e32 v135, v134, v133
	v_fma_f32 v136, -v123, v135, v134
; __device__ __forceinline__ float sigmoidf_(float x) { return 1.0f / (1.0f + __expf(-x)); }
; __device__ __forceinline__ f32x4 cv_bf4(const u32x2 w) { return (f32x4){bflo(w.x), bfhi(w.x), bflo(w.y), bfhi(w.y)}; }
; __device__ __forceinline__ void scan_finish(const ScanPtrs& Q, int J, int ci, unsigned char* buf, int ltid, const LStage& L, int toff) {
;     ...
;         r = r + (rp - r) * *(const f32x4*)mu; k0 = k0 + (kp - k0) * *(const f32x4*)(mu + 512); v = v + (vp - v) * *(const f32x4*)(mu + 1024);
;         const f32x4 kk = k0 * *(const f32x4*)(Q.k_k + gc);
;         const float ss = allsum16((kk[0] * kk[0] + kk[1] * kk[1]) + (kk[2] * kk[2] + kk[3] * kk[3]));
;         const float inv = 1.0f / fmaxf(sqrtf(ss), 1e-12f);
;         const f32x4 kkn = kk * inv;
;         const f32x4 dw = cv_bf4(L.sw) + *(const f32x4*)(Q.decay0 + gc);
;         const f32x4 da = cv_bf4(L.sa) + *(const f32x4*)(Q.a0 + gc);
;         f32x4 dec, ain;
; #pragma unroll
;         for (int j = 0; j < 4; ++j) { dec[j] = __expf(-0.60653066f * sigmoidf_(dw[j])); ain[j] = sigmoidf_(da[j]); }
;         const f32x4 ka = *(const f32x4*)(Q.k_a + gc);
;         const f32x4 kf = k0 * (1.0f + (ain - 1.0f) * ka);
;         const f32x4 rkw = *(const f32x4*)(Q.r_k + gc);
;         const f32x4 pr = r * kf * rkw;
;         const float rk = allsum16((pr[0] + pr[1]) + (pr[2] + pr[3]));
;         unsigned char* tb = buf + tt * SC_TOKB + c * 4;
;         *(f32x4*)(tb) = -kkn; *(f32x4*)(tb + 256) = dec; *(f32x4*)(tb + 512) = kkn * ain; *(f32x4*)(tb + 768) = kf; *(f32x4*)(tb + 1024) = r;
;         if ((c >> 4) == jb.rs) *(f32x4*)(buf + tt * SC_TOKB + 1280 + (c & 15) * 4) = v;
;         if (jb.rs == 0 && c == 0) Q.rk[(size_t)tok * 8 + jb.h] = rk;
	v_fmac_f32_e32 v135, v136, v133
	v_fma_f32 v123, -v123, v135, v134
	v_div_fmas_f32 v123, v123, v133, v135
	v_add_f32_e32 v41, 1.0, v41
	v_div_fixup_f32 v40, v123, v40, 1.0
	v_div_scale_f32 v123, s[8:9], v41, v41, 1.0
	v_rcp_f32_e32 v133, v123
	v_mul_f32_e32 v35, 0xbfb8aa3b, v35
	v_exp_f32_e32 v34, v34
	v_exp_f32_e32 v35, v35
	v_fma_f32 v134, -v123, v133, 1.0
	v_fmac_f32_e32 v133, v134, v133
	v_div_scale_f32 v134, vcc, 1.0, v41, 1.0
	v_mul_f32_e32 v135, v134, v133
	v_fma_f32 v136, -v123, v135, v134
	v_fmac_f32_e32 v135, v136, v133
	v_fma_f32 v123, -v123, v135, v134
	v_div_fmas_f32 v123, v123, v133, v135
	v_pk_add_f32 v[34:35], v[34:35], 1.0 op_sel_hi:[1,0]
	v_div_fixup_f32 v41, v123, v41, 1.0
	v_div_scale_f32 v123, s[8:9], v35, v35, 1.0
	v_rcp_f32_e32 v133, v123
	v_add_f32_e32 v36, v196, v147
	v_add_f32_e32 v37, v197, v148
	v_mul_f32_e32 v36, 0xbfb8aa3b, v36
	v_fma_f32 v134, -v123, v133, 1.0
	v_fmac_f32_e32 v133, v134, v133
	v_div_scale_f32 v134, vcc, 1.0, v35, 1.0
	v_mul_f32_e32 v135, v134, v133
	v_fma_f32 v136, -v123, v135, v134
	v_fmac_f32_e32 v135, v136, v133
	v_fma_f32 v123, -v123, v135, v134
	v_div_scale_f32 v134, s[8:9], v34, v34, 1.0
	v_rcp_f32_e32 v136, v134
	v_mul_f32_e32 v37, 0xbfb8aa3b, v37
	v_exp_f32_e32 v36, v36
	v_exp_f32_e32 v37, v37
	v_div_fmas_f32 v123, v123, v133, v135
	v_div_fixup_f32 v135, v123, v35, 1.0
	v_fma_f32 v35, -v134, v136, 1.0
	v_fmac_f32_e32 v136, v35, v136
	v_div_scale_f32 v35, vcc, 1.0, v34, 1.0
	v_mul_f32_e32 v123, v35, v136
	v_pk_add_f32 v[36:37], v[36:37], 1.0 op_sel_hi:[1,0]
	v_fma_f32 v133, -v134, v123, v35
	v_fmac_f32_e32 v123, v133, v136
	v_div_scale_f32 v133, s[8:9], v37, v37, 1.0
	v_rcp_f32_e32 v137, v133
	v_fma_f32 v35, -v134, v123, v35
	v_div_fmas_f32 v35, v35, v136, v123
	v_div_fixup_f32 v134, v35, v34, 1.0
	v_fma_f32 v34, -v133, v137, 1.0
	v_fmac_f32_e32 v137, v34, v137
	v_div_scale_f32 v34, vcc, 1.0, v37, 1.0
	v_mul_f32_e32 v35, v34, v137
	v_fma_f32 v123, -v133, v35, v34
	v_fmac_f32_e32 v35, v123, v137
	v_div_scale_f32 v123, s[8:9], v36, v36, 1.0
	v_fma_f32 v34, -v133, v35, v34
	v_rcp_f32_e32 v133, v123
	v_div_fmas_f32 v34, v34, v137, v35
	v_div_fixup_f32 v37, v34, v37, 1.0
	v_mul_f32_e32 v38, 0xbf1b4598, v38
	v_fma_f32 v34, -v123, v133, 1.0
	v_fmac_f32_e32 v133, v34, v133
	v_div_scale_f32 v34, vcc, 1.0, v36, 1.0
	v_mul_f32_e32 v35, v34, v133
	v_fma_f32 v136, -v123, v35, v34
	v_fmac_f32_e32 v35, v136, v133
	v_fma_f32 v34, -v123, v35, v34
	v_div_fmas_f32 v34, v34, v133, v35
	v_div_fixup_f32 v36, v34, v36, 1.0
	s_waitcnt vmcnt(0)
	v_pk_fma_f32 v[34:35], v[48:49], v[204:205], v[92:93]
	v_pk_fma_f32 v[32:33], v[46:47], v[202:203], v[20:21]
	v_pk_add_f32 v[20:21], v[36:37], -1.0 op_sel_hi:[1,0]
	v_pk_add_f32 v[30:31], v[134:135], -1.0 op_sel_hi:[1,0]
	s_waitcnt vmcnt(0)
	v_pk_fma_f32 v[20:21], v[208:209], v[20:21], 1.0 op_sel_hi:[1,1,0]
	v_pk_fma_f32 v[30:31], v[206:207], v[30:31], 1.0 op_sel_hi:[1,1,0]
	v_pk_mul_f32 v[44:45], v[44:45], v[20:21]
	v_pk_mul_f32 v[42:43], v[42:43], v[30:31]
	v_pk_mul_f32 v[30:31], v[34:35], v[44:45]
	v_pk_mul_f32 v[20:21], v[32:33], v[42:43]
	s_waitcnt vmcnt(0)
	v_pk_mul_f32 v[30:31], v[212:213], v[30:31]
	v_pk_mul_f32 v[20:21], v[210:211], v[20:21]
	v_mul_f32_e32 v39, 0xbf1b4598, v39
	v_mul_f32_e32 v40, 0xbf1b4598, v40
	v_mul_f32_e32 v41, 0xbf1b4598, v41
	v_add_f32_e32 v20, v20, v21
	v_add_f32_e32 v21, v30, v31
	v_mul_f32_e32 v38, 0x3fb8aa3b, v38
	v_mul_f32_e32 v39, 0x3fb8aa3b, v39
	v_mul_f32_e32 v40, 0x3fb8aa3b, v40
	v_mul_f32_e32 v41, 0x3fb8aa3b, v41
	v_add_f32_e32 v20, v20, v21
	v_exp_f32_e32 v38, v38
	v_exp_f32_e32 v39, v39
	v_exp_f32_e32 v40, v40
	v_exp_f32_e32 v41, v41
	v_add_f32_dpp v20, v20, v20 quad_perm:[1,0,3,2] row_mask:0xf bank_mask:0xf bound_ctrl:1
	v_add_u32_e32 v30, s6, v99
	v_mov_b32_e32 v21, 0
	v_add_f32_dpp v20, v20, v20 quad_perm:[2,3,0,1] row_mask:0xf bank_mask:0xf bound_ctrl:1
	v_add_u32_e32 v31, v30, v100
	v_pk_mul_f32 v[48:49], v[126:127], v[132:133] op_sel_hi:[1,0]
	v_add_f32_dpp v20, v20, v20 row_half_mirror row_mask:0xf bank_mask:0xf bound_ctrl:1
	v_pk_mul_f32 v[46:47], v[124:125], v[132:133] op_sel_hi:[1,0]
	ds_write_b128 v31, v[46:49]
	ds_write_b128 v31, v[38:41] offset:256
	v_mov_b32_dpp v21, v20 row_mirror row_mask:0xf bank_mask:0xf
	v_pk_mul_f32 v[38:39], v[48:49], v[36:37] neg_lo:[1,0] neg_hi:[1,0]
	v_pk_mul_f32 v[36:37], v[46:47], v[134:135] neg_lo:[1,0] neg_hi:[1,0]
	v_cmp_eq_u32_e32 vcc, v101, v121
	ds_write_b128 v31, v[36:39] offset:512
	ds_write_b128 v31, v[42:45] offset:768
	ds_write_b128 v31, v[32:35] offset:1024
	s_and_saveexec_b64 s[18:19], vcc
	s_cbranch_execz .LBB0_490
	v_lshl_add_u64 v[32:33], s[30:31], 0, v[18:19]
	v_add_co_u32_e32 v32, vcc, 0x1000, v32
	v_lshlrev_b32_e32 v36, 16, v72
	s_nop 0
	v_addc_co_u32_e32 v33, vcc, 0, v33, vcc
	v_and_b32_e32 v37, 0xffff0000, v72
	v_lshlrev_b32_e32 v38, 16, v73
	v_and_b32_e32 v39, 0xffff0000, v73
	v_sub_f32_e32 v29, v29, v39
	v_sub_f32_e32 v28, v28, v38
	v_sub_f32_e32 v27, v27, v37
	v_sub_f32_e32 v26, v26, v36
	v_add_u32_e32 v18, v30, v102
	s_waitcnt vmcnt(0)
	v_pk_fma_f32 v[26:27], v[26:27], v[214:215], v[36:37]
	v_pk_fma_f32 v[28:29], v[28:29], v[216:217], v[38:39]
	ds_write_b128 v18, v[26:29] offset:1280

; __device__ __forceinline__ float sigmoidf_(float x) { return 1.0f / (1.0f + __expf(-x)); }
; __device__ __forceinline__ f32x4 cv_bf4(const u32x2 w) { return (f32x4){bflo(w.x), bfhi(w.x), bflo(w.y), bfhi(w.y)}; }
; __device__ __forceinline__ void scan_finish(const ScanPtrs& Q, int J, int ci, unsigned char* buf, int ltid, const LStage& L, int toff) {
;     ...
;         const float* mu = Q.mu + gc;
;         r = r + (rp - r) * *(const f32x4*)mu; k0 = k0 + (kp - k0) * *(const f32x4*)(mu + 512); v = v + (vp - v) * *(const f32x4*)(mu + 1024);
;         const f32x4 kk = k0 * *(const f32x4*)(Q.k_k + gc);
;         const float ss = allsum16((kk[0] * kk[0] + kk[1] * kk[1]) + (kk[2] * kk[2] + kk[3] * kk[3]));
;         const float inv = 1.0f / fmaxf(sqrtf(ss), 1e-12f);
;         const f32x4 kkn = kk * inv;
;         const f32x4 dw = cv_bf4(L.sw) + *(const f32x4*)(Q.decay0 + gc);
;         const f32x4 da = cv_bf4(L.sa) + *(const f32x4*)(Q.a0 + gc);
;         f32x4 dec, ain;
; #pragma unroll
;         for (int j = 0; j < 4; ++j) { dec[j] = __expf(-0.60653066f * sigmoidf_(dw[j])); ain[j] = sigmoidf_(da[j]); }
;         const f32x4 ka = *(const f32x4*)(Q.k_a + gc);
;         const f32x4 kf = k0 * (1.0f + (ain - 1.0f) * ka);
;         const f32x4 rkw = *(const f32x4*)(Q.r_k + gc);
;         const f32x4 pr = r * kf * rkw;
;         const float rk = allsum16((pr[0] + pr[1]) + (pr[2] + pr[3]));
;         unsigned char* tb = buf + tt * SC_TOKB + c * 4;
;         *(f32x4*)(tb) = -kkn; *(f32x4*)(tb + 256) = dec; *(f32x4*)(tb + 512) = kkn * ain; *(f32x4*)(tb + 768) = kf; *(f32x4*)(tb + 1024) = r;
.LBB0_495:
	s_or_b64 exec, exec, s[16:17]
	v_lshl_or_b32 v18, v91, 8, v100
	s_waitcnt vmcnt(1)
	v_lshlrev_b32_e32 v134, 16, v60
	v_and_b32_e32 v135, 0xffff0000, v60
	v_lshlrev_b32_e32 v136, 16, v61
	v_and_b32_e32 v137, 0xffff0000, v61
	v_sub_f32_e32 v139, v92, v135
	v_sub_f32_e32 v138, v52, v134
	v_sub_f32_e32 v93, v93, v137
	v_sub_f32_e32 v92, v53, v136
	s_waitcnt vmcnt(1)
	v_lshlrev_b32_e32 v140, 16, v78
	v_and_b32_e32 v141, 0xffff0000, v78
	v_lshlrev_b32_e32 v142, 16, v79
	s_waitcnt vmcnt(1)
	v_lshlrev_b32_e32 v146, 16, v80
	v_and_b32_e32 v143, 0xffff0000, v79
	v_and_b32_e32 v147, 0xffff0000, v80
	v_lshlrev_b32_e32 v148, 16, v81
	v_and_b32_e32 v149, 0xffff0000, v81
	v_lshlrev_b32_e32 v20, 16, v56
	v_and_b32_e32 v21, 0xffff0000, v56
	v_lshlrev_b32_e32 v42, 16, v57
	v_and_b32_e32 v43, 0xffff0000, v57
	v_sub_f32_e32 v45, v45, v21
	v_sub_f32_e32 v44, v44, v20
	v_sub_f32_e32 v47, v47, v43
	v_sub_f32_e32 v46, v46, v42
	s_waitcnt vmcnt(1)
	v_pk_fma_f32 v[40:41], v[92:93], v[188:189], v[136:137]
	v_pk_fma_f32 v[38:39], v[138:139], v[186:187], v[134:135]
	s_waitcnt vmcnt(1)
	v_add_f32_e32 v34, v190, v140
	v_add_f32_e32 v35, v191, v141
	s_waitcnt vmcnt(1)
	v_pk_mul_f32 v[52:53], v[40:41], v[200:201]
	v_pk_mul_f32 v[92:93], v[38:39], v[198:199]
	v_mul_f32_e32 v124, 0xbfb8aa3b, v34
	v_mul_f32_e32 v125, 0xbfb8aa3b, v35
	v_pk_mul_f32 v[34:35], v[52:53], v[52:53]
	v_pk_mul_f32 v[122:123], v[92:93], v[92:93]
	v_exp_f32_e32 v134, v124
	v_exp_f32_e32 v135, v125
	v_pk_mov_b32 v[124:125], v[122:123], v[34:35] op_sel:[1,0]
	v_mov_b32_e32 v123, v35
	v_pk_add_f32 v[34:35], v[124:125], v[122:123]
	v_add_f32_e32 v123, 1.0, v135
	v_add_f32_e32 v34, v34, v35
	v_add_f32_e32 v35, 1.0, v134
	v_div_scale_f32 v122, s[8:9], v35, v35, 1.0
	v_add_f32_dpp v34, v34, v34 quad_perm:[1,0,3,2] row_mask:0xf bank_mask:0xf bound_ctrl:1
	v_div_scale_f32 v125, s[8:9], v123, v123, 1.0
	s_nop 0
	v_add_f32_dpp v34, v34, v34 quad_perm:[2,3,0,1] row_mask:0xf bank_mask:0xf bound_ctrl:1
	v_rcp_f32_e32 v135, v122
	v_rcp_f32_e32 v136, v125
	v_add_f32_dpp v34, v34, v34 row_half_mirror row_mask:0xf bank_mask:0xf bound_ctrl:1
	v_div_scale_f32 v124, s[16:17], 1.0, v35, 1.0
	s_nop 0
	v_add_f32_dpp v34, v34, v34 row_mirror row_mask:0xf bank_mask:0xf bound_ctrl:1
	v_mul_f32_e32 v137, 0x4f800000, v34
	v_cmp_gt_f32_e32 vcc, s78, v34
	v_fma_f32 v138, -v122, v135, 1.0
	v_fma_f32 v139, -v125, v136, 1.0
	v_cndmask_b32_e32 v34, v34, v137, vcc
	v_sqrt_f32_e32 v137, v34
	v_fmac_f32_e32 v135, v138, v135
	v_div_scale_f32 v134, s[18:19], 1.0, v123, 1.0
	v_fmac_f32_e32 v136, v139, v136
	v_mul_f32_e32 v138, v124, v135
	v_add_f32_e32 v36, v192, v142
	v_mul_f32_e32 v139, v134, v136
	v_fma_f32 v140, -v122, v138, v124
	v_add_u32_e32 v142, -1, v137
	v_add_f32_e32 v30, v194, v146
	v_fma_f32 v141, -v125, v139, v134
	v_add_u32_e32 v146, 1, v137
	v_fmac_f32_e32 v138, v140, v135
	v_fma_f32 v140, -v142, v137, v34
	v_fmac_f32_e32 v139, v141, v136
	v_fma_f32 v141, -v146, v137, v34
	v_cmp_ge_f32_e64 s[20:21], 0, v140
	v_fma_f32 v124, -v122, v138, v124
	v_fma_f32 v125, -v125, v139, v134
	v_cndmask_b32_e64 v122, v137, v142, s[20:21]
	v_cmp_lt_f32_e64 s[20:21], 0, v141
	v_mul_f32_e32 v36, 0xbfb8aa3b, v36
	v_exp_f32_e32 v36, v36
	v_cndmask_b32_e64 v122, v122, v146, s[20:21]
	v_mul_f32_e32 v137, 0x37800000, v122
	v_cndmask_b32_e32 v122, v122, v137, vcc
	v_cmp_class_f32_e32 vcc, v34, v118
	v_add_f32_e32 v36, 1.0, v36
	v_add_f32_e32 v37, v193, v143
	v_cndmask_b32_e32 v34, v122, v34, vcc
	v_max_f32_e32 v34, 0x2b8cbccc, v34
	v_div_scale_f32 v122, s[8:9], v34, v34, -1.0
	v_rcp_f32_e32 v137, v122
	v_div_scale_f32 v134, vcc, -1.0, v34, -1.0
	v_mul_f32_e32 v37, 0xbfb8aa3b, v37
	v_fma_f32 v140, -v122, v137, 1.0
	v_fmac_f32_e32 v137, v140, v137
	v_mul_f32_e32 v140, v134, v137
	v_fma_f32 v141, -v122, v140, v134
	v_fmac_f32_e32 v140, v141, v137
	v_fma_f32 v122, -v122, v140, v134
	v_div_fmas_f32 v122, v122, v137, v140
	s_mov_b64 vcc, s[16:17]
	v_div_fixup_f32 v122, v122, v34, -1.0
	v_div_fmas_f32 v34, v124, v135, v138
	s_mov_b64 vcc, s[18:19]
	v_div_fixup_f32 v34, v34, v35, 1.0
	v_div_fmas_f32 v35, v125, v136, v139
	v_div_fixup_f32 v35, v35, v123, 1.0
	v_div_scale_f32 v123, s[8:9], v36, v36, 1.0
	v_rcp_f32_e32 v124, v123
	v_exp_f32_e32 v37, v37
	v_add_f32_e32 v31, v195, v147
	v_mul_f32_e32 v30, 0xbfb8aa3b, v30
	v_fma_f32 v125, -v123, v124, 1.0
	v_fmac_f32_e32 v124, v125, v124
	v_div_scale_f32 v125, vcc, 1.0, v36, 1.0
	v_mul_f32_e32 v134, v125, v124
	v_fma_f32 v135, -v123, v134, v125
	v_fmac_f32_e32 v134, v135, v124
	v_fma_f32 v123, -v123, v134, v125
	v_div_fmas_f32 v123, v123, v124, v134
	v_add_f32_e32 v37, 1.0, v37
	v_div_fixup_f32 v36, v123, v36, 1.0
	v_div_scale_f32 v123, s[8:9], v37, v37, 1.0
	v_rcp_f32_e32 v124, v123
	v_mul_f32_e32 v31, 0xbfb8aa3b, v31
	v_exp_f32_e32 v30, v30
	v_exp_f32_e32 v31, v31
	v_fma_f32 v125, -v123, v124, 1.0
	v_fmac_f32_e32 v124, v125, v124
	v_div_scale_f32 v125, vcc, 1.0, v37, 1.0
	v_mul_f32_e32 v134, v125, v124
	v_fma_f32 v135, -v123, v134, v125
	v_fmac_f32_e32 v134, v135, v124
	v_fma_f32 v123, -v123, v134, v125
	v_div_fmas_f32 v123, v123, v124, v134
	v_pk_add_f32 v[30:31], v[30:31], 1.0 op_sel_hi:[1,0]
	v_div_fixup_f32 v37, v123, v37, 1.0
	v_div_scale_f32 v123, s[8:9], v31, v31, 1.0
	v_rcp_f32_e32 v124, v123
	v_add_f32_e32 v32, v196, v148
	v_add_f32_e32 v33, v197, v149
	v_mul_f32_e32 v32, 0xbfb8aa3b, v32
	v_fma_f32 v125, -v123, v124, 1.0
	v_fmac_f32_e32 v124, v125, v124
	v_div_scale_f32 v125, vcc, 1.0, v31, 1.0
	v_mul_f32_e32 v134, v125, v124
	v_fma_f32 v135, -v123, v134, v125
	v_fmac_f32_e32 v134, v135, v124
	v_div_scale_f32 v135, s[8:9], v30, v30, 1.0
	v_rcp_f32_e32 v136, v135
	v_mul_f32_e32 v33, 0xbfb8aa3b, v33
	v_fma_f32 v123, -v123, v134, v125
	v_exp_f32_e32 v32, v32
	v_exp_f32_e32 v33, v33
	v_div_fmas_f32 v123, v123, v124, v134
	v_div_fixup_f32 v125, v123, v31, 1.0
	v_fma_f32 v31, -v135, v136, 1.0
	v_fmac_f32_e32 v136, v31, v136
	v_div_scale_f32 v31, vcc, 1.0, v30, 1.0
	v_mul_f32_e32 v123, v31, v136
	v_pk_add_f32 v[32:33], v[32:33], 1.0 op_sel_hi:[1,0]
	v_fma_f32 v124, -v135, v123, v31
	v_fmac_f32_e32 v123, v124, v136
	v_div_scale_f32 v134, s[8:9], v33, v33, 1.0
	v_fma_f32 v31, -v135, v123, v31
	v_rcp_f32_e32 v135, v134
	v_div_fmas_f32 v31, v31, v136, v123
	v_div_fixup_f32 v124, v31, v30, 1.0
	v_mul_f32_e32 v34, 0xbf1b4598, v34
	v_fma_f32 v30, -v134, v135, 1.0
	v_fmac_f32_e32 v135, v30, v135
	v_div_scale_f32 v30, vcc, 1.0, v33, 1.0
	v_mul_f32_e32 v31, v30, v135
	v_fma_f32 v123, -v134, v31, v30
	v_fmac_f32_e32 v31, v123, v135
	v_div_scale_f32 v123, s[8:9], v32, v32, 1.0
	v_fma_f32 v30, -v134, v31, v30
	v_rcp_f32_e32 v134, v123
	v_div_fmas_f32 v30, v30, v135, v31
	v_div_fixup_f32 v33, v30, v33, 1.0
	v_mul_f32_e32 v35, 0xbf1b4598, v35
	v_fma_f32 v30, -v123, v134, 1.0
	v_fmac_f32_e32 v134, v30, v134
	v_div_scale_f32 v30, vcc, 1.0, v32, 1.0
	v_mul_f32_e32 v31, v30, v134
	v_fma_f32 v135, -v123, v31, v30
	v_fmac_f32_e32 v31, v135, v134
	v_fma_f32 v30, -v123, v31, v30
	v_div_fmas_f32 v30, v30, v134, v31
	v_div_fixup_f32 v32, v30, v32, 1.0
	s_waitcnt vmcnt(1)
; __device__ __forceinline__ void scan_finish(const ScanPtrs& Q, int J, int ci, unsigned char* buf, int ltid, const LStage& L, int toff) {
;     ...
;         const f32x4 kf = k0 * (1.0f + (ain - 1.0f) * ka);
;         const f32x4 rkw = *(const f32x4*)(Q.r_k + gc);
;         const f32x4 pr = r * kf * rkw;
;         const float rk = allsum16((pr[0] + pr[1]) + (pr[2] + pr[3]));
;         unsigned char* tb = buf + tt * SC_TOKB + c * 4;
;         *(f32x4*)(tb) = -kkn; *(f32x4*)(tb + 256) = dec; *(f32x4*)(tb + 512) = kkn * ain; *(f32x4*)(tb + 768) = kf; *(f32x4*)(tb + 1024) = r;
;         if ((c >> 4) == jb.rs) *(f32x4*)(buf + tt * SC_TOKB + 1280 + (c & 15) * 4) = v;
	v_pk_fma_f32 v[30:31], v[46:47], v[204:205], v[42:43]
	v_pk_fma_f32 v[28:29], v[44:45], v[202:203], v[20:21]
	v_pk_add_f32 v[20:21], v[32:33], -1.0 op_sel_hi:[1,0]
	v_pk_add_f32 v[26:27], v[124:125], -1.0 op_sel_hi:[1,0]
	s_waitcnt vmcnt(1)
	v_pk_fma_f32 v[20:21], v[208:209], v[20:21], 1.0 op_sel_hi:[1,1,0]
	v_pk_fma_f32 v[26:27], v[206:207], v[26:27], 1.0 op_sel_hi:[1,1,0]
	v_pk_mul_f32 v[40:41], v[40:41], v[20:21]
	v_pk_mul_f32 v[38:39], v[38:39], v[26:27]
	v_pk_mul_f32 v[26:27], v[30:31], v[40:41]
	v_pk_mul_f32 v[20:21], v[28:29], v[38:39]
	s_waitcnt vmcnt(1)
	v_pk_mul_f32 v[26:27], v[212:213], v[26:27]
	v_pk_mul_f32 v[20:21], v[210:211], v[20:21]
	v_mul_f32_e32 v36, 0xbf1b4598, v36
	v_mul_f32_e32 v37, 0xbf1b4598, v37
	v_add_f32_e32 v20, v20, v21
	v_add_f32_e32 v21, v26, v27
	v_mul_f32_e32 v34, 0x3fb8aa3b, v34
	v_mul_f32_e32 v35, 0x3fb8aa3b, v35
	v_mul_f32_e32 v36, 0x3fb8aa3b, v36
	v_mul_f32_e32 v37, 0x3fb8aa3b, v37
	v_add_f32_e32 v20, v20, v21
	v_exp_f32_e32 v34, v34
	v_exp_f32_e32 v35, v35
	v_exp_f32_e32 v36, v36
	v_exp_f32_e32 v37, v37
	v_add_f32_dpp v20, v20, v20 quad_perm:[1,0,3,2] row_mask:0xf bank_mask:0xf bound_ctrl:1
	v_add_u32_e32 v26, s6, v105
	v_mov_b32_e32 v21, 0
	v_add_f32_dpp v20, v20, v20 quad_perm:[2,3,0,1] row_mask:0xf bank_mask:0xf bound_ctrl:1
	v_add_u32_e32 v27, v26, v100
	v_pk_mul_f32 v[44:45], v[52:53], v[122:123] op_sel_hi:[1,0]
	v_add_f32_dpp v20, v20, v20 row_half_mirror row_mask:0xf bank_mask:0xf bound_ctrl:1
	v_pk_mul_f32 v[42:43], v[92:93], v[122:123] op_sel_hi:[1,0]
	ds_write_b128 v27, v[42:45]
	ds_write_b128 v27, v[34:37] offset:256
	v_mov_b32_dpp v21, v20 row_mirror row_mask:0xf bank_mask:0xf
	v_pk_mul_f32 v[34:35], v[44:45], v[32:33] neg_lo:[1,0] neg_hi:[1,0]
	v_pk_mul_f32 v[32:33], v[42:43], v[124:125] neg_lo:[1,0] neg_hi:[1,0]
	v_cmp_eq_u32_e32 vcc, v101, v121
	ds_write_b128 v27, v[32:35] offset:512
	ds_write_b128 v27, v[38:41] offset:768
	ds_write_b128 v27, v[28:31] offset:1024
	s_and_saveexec_b64 s[16:17], vcc
	s_cbranch_execz .LBB0_497
	v_lshl_add_u64 v[28:29], s[30:31], 0, v[18:19]
	v_add_co_u32_e32 v28, vcc, 0x1000, v28
	v_lshlrev_b32_e32 v32, 16, v68
	s_nop 0
	v_addc_co_u32_e32 v29, vcc, 0, v29, vcc
	v_and_b32_e32 v33, 0xffff0000, v68
	v_lshlrev_b32_e32 v34, 16, v69
	v_and_b32_e32 v35, 0xffff0000, v69
	v_add_u32_e32 v18, v26, v102
	v_sub_f32_e32 v37, v51, v35
	v_sub_f32_e32 v36, v50, v34
	v_sub_f32_e32 v27, v49, v33
	v_sub_f32_e32 v26, v48, v32
	s_waitcnt vmcnt(1)
	v_pk_fma_f32 v[26:27], v[26:27], v[214:215], v[32:33]
	v_pk_fma_f32 v[28:29], v[36:37], v[216:217], v[34:35]
	ds_write_b128 v18, v[26:29] offset:1280

; #define KP(f) ((decltype(Params::f))karg_ptr<(int)offsetof(Params, f)>())
; __device__ void phase_scan(int l, unsigned char* lds) {
;     int tid_ = threadIdx.x; asm volatile("" : "+v"(tid_));
;     const int tid = tid_, wid = tid >> 6, lane = tid & 63, G = gridDim.x;
;     const bool loader = wid >= 4;
;     if (!loader) __builtin_amdgcn_s_setprio(3);
;     ScanPtrs Q;
;     Q.z = KP(z); Q.sw = KP(xb) + (size_t)T_ALL * 512; Q.sa = KP(sc_a); Q.st_shift = KP(state_shift) + (size_t)l * NSB * DSH; Q.mu = KP(mu_shift) + (size_t)l * DSH;
;     Q.k_k = KP(k_k) + (size_t)l * 512; Q.k_a = KP(k_a) + (size_t)l * 512; Q.r_k = KP(r_k) + (size_t)l * 512; Q.decay0 = KP(decay0) + (size_t)l * 512; Q.a0 = KP(a0) + (size_t)l * 512; Q.rk = KP(rk);
;     bf16_t* ybuf = KP(xb);
;     const float* st_wkv = KP(state_wkv); float* out = KP(out);
;     int J = (G % 8 == 0) ? (int)(blockIdx.x % 8) * (G / 8) + (int)(blockIdx.x / 8) : (int)blockIdx.x, ci = 0, it = 0;
;     int Ji = J, cis = 0;
;     int Jg = J, cg_ = 0;
;     LStage L, L2;
;     f32x2 s01 = (f32x2){0.f, 0.f}, s23 = s01;
;     f32x4 s_pref = (f32x4){0.f, 0.f, 0.f, 0.f};
;     if (!loader && J >= 256 && J < NJOBS) { const Job j0 = job_decode(J, 0); s_pref = *(const f32x4*)(st_wkv + (((((size_t)l * NSB + j0.seq) * 8 + j0.h) * 64 + j0.rs * 16 + (wid * 4 + (lane >> 4))) * 64 + (lane & 15) * 4)); }
.LBB0_1542:
	s_or_b64 exec, exec, s[10:11]
	s_mov_b32 s6, s2
	s_mov_b32 s7, s46
	v_mov_b32_e32 v53, v166
	s_waitcnt lgkmcnt(0)
	s_barrier
	s_nop 0
	v_ashrrev_i32_e32 v52, 6, v53
	s_mov_b32 s98, -1
	v_cmp_lt_i32_e64 s[10:11], 3, v52
	v_cmp_gt_i32_e64 s[12:13], 4, v52
	s_and_saveexec_b64 s[14:15], s[12:13]
	s_setprio 3
	s_or_b64 exec, exec, s[14:15]
	s_load_dwordx2 s[22:23], s[0:1], 0x130
	s_waitcnt lgkmcnt(0)
	s_load_dwordx2 s[16:17], s[0:1], 0x120
	s_waitcnt lgkmcnt(0)
	s_load_dwordx2 s[24:25], s[0:1], 0x140
	s_waitcnt lgkmcnt(0)
	s_load_dwordx2 s[18:19], s[0:1], 16
	s_waitcnt lgkmcnt(0)
	s_load_dwordx2 s[14:15], s[0:1], 56
	s_waitcnt lgkmcnt(0)
	s_load_dwordx2 s[26:27], s[0:1], 0x68
	s_waitcnt lgkmcnt(0)
	s_load_dwordx2 s[28:29], s[0:1], 0x70
	s_waitcnt lgkmcnt(0)
	s_load_dwordx2 s[30:31], s[0:1], 0x78
	s_waitcnt lgkmcnt(0)
	s_load_dwordx2 s[34:35], s[0:1], 64
	s_waitcnt lgkmcnt(0)
	s_load_dwordx2 s[36:37], s[0:1], 0x50
	s_waitcnt lgkmcnt(0)
	s_load_dwordx2 s[38:39], s[0:1], 0x150
	s_waitcnt lgkmcnt(0)
	s_load_dwordx2 s[40:41], s[0:1], 0x120
	s_waitcnt lgkmcnt(0)
	s_load_dwordx2 s[20:21], s[0:1], 32
	s_waitcnt lgkmcnt(0)
	s_load_dwordx2 s[42:43], s[0:1], 0xd8
	s_waitcnt lgkmcnt(0)
	v_readlane_b32 s6, v230, 6
	v_readlane_b32 s7, v230, 7
	s_and_b64 vcc, exec, s[6:7]
	s_mov_b32 s53, s2
	s_cbranch_vccnz .LBB0_1546
	s_and_b32 s6, s2, 7
	s_ashr_i32 s7, s46, 3
	s_mul_i32 s6, s7, s6
	s_lshr_b32 s7, s2, 3
	s_add_i32 s53, s6, s7

; __device__ __forceinline__ float sigmoidf_(float x) { return 1.0f / (1.0f + __expf(-x)); }
; __device__ __forceinline__ f32x4 cv_bf4(const u32x2 w) { return (f32x4){bflo(w.x), bfhi(w.x), bflo(w.y), bfhi(w.y)}; }
; __device__ __forceinline__ void scan_finish(const ScanPtrs& Q, int J, int ci, unsigned char* buf, int ltid, const LStage& L, int toff) {
;     ...
;         const float* mu = Q.mu + gc;
;         r = r + (rp - r) * *(const f32x4*)mu; k0 = k0 + (kp - k0) * *(const f32x4*)(mu + 512); v = v + (vp - v) * *(const f32x4*)(mu + 1024);
;         const f32x4 kk = k0 * *(const f32x4*)(Q.k_k + gc);
;         const float ss = allsum16((kk[0] * kk[0] + kk[1] * kk[1]) + (kk[2] * kk[2] + kk[3] * kk[3]));
;         const float inv = 1.0f / fmaxf(sqrtf(ss), 1e-12f);
;         const f32x4 kkn = kk * inv;
;         const f32x4 dw = cv_bf4(L.sw) + *(const f32x4*)(Q.decay0 + gc);
;         const f32x4 da = cv_bf4(L.sa) + *(const f32x4*)(Q.a0 + gc);
;         f32x4 dec, ain;
; #pragma unroll
;         for (int j = 0; j < 4; ++j) { dec[j] = __expf(-0.60653066f * sigmoidf_(dw[j])); ain[j] = sigmoidf_(da[j]); }
;         const f32x4 ka = *(const f32x4*)(Q.k_a + gc);
;         const f32x4 kf = k0 * (1.0f + (ain - 1.0f) * ka);
;         const f32x4 rkw = *(const f32x4*)(Q.r_k + gc);
;         const f32x4 pr = r * kf * rkw;
;         const float rk = allsum16((pr[0] + pr[1]) + (pr[2] + pr[3]));
;         unsigned char* tb = buf + tt * SC_TOKB + c * 4;
;         *(f32x4*)(tb) = -kkn; *(f32x4*)(tb + 256) = dec; *(f32x4*)(tb + 512) = kkn * ain; *(f32x4*)(tb + 768) = kf; *(f32x4*)(tb + 1024) = r;
;         if ((c >> 4) == jb.rs) *(f32x4*)(buf + tt * SC_TOKB + 1280 + (c & 15) * 4) = v;
.LBB0_1629:
	s_or_b64 exec, exec, s[16:17]
	v_lshl_or_b32 v18, v91, 8, v100
	v_readfirstlane_b32 s99, v91
	s_nop 3
	s_cmp_eq_u32 s99, s98
	s_cbranch_scc1 .Lprm_ok_1
	s_mov_b32 s98, s99
	s_lshl_b32 s99, s99, 8
	s_mov_b64 s[100:101], exec
	s_mov_b64 exec, -1
	v_or_b32_e32 v229, s99, v100
	global_load_dwordx4 v[186:189], v229, s[58:59] offset:2048
	global_load_dwordx4 v[190:193], v229, s[34:35] offset:2048
	global_load_dwordx4 v[194:197], v229, s[36:37] offset:2048
	global_load_dwordx4 v[198:201], v229, s[26:27] offset:2048
	global_load_dwordx4 v[202:205], v229, s[58:59]
	global_load_dwordx4 v[206:209], v229, s[28:29] offset:2048
	global_load_dwordx4 v[210:213], v229, s[30:31] offset:2048
	v_add_u32_e32 v228, 0x1000, v229
	global_load_dwordx4 v[214:217], v228, s[58:59]
	s_waitcnt vmcnt(0)
	s_mov_b64 exec, s[100:101]
.Lprm_ok_1:
	s_waitcnt vmcnt(3)
	v_lshlrev_b32_e32 v132, 16, v70
	v_and_b32_e32 v133, 0xffff0000, v70
	v_lshlrev_b32_e32 v134, 16, v71
	v_and_b32_e32 v135, 0xffff0000, v71
	v_sub_f32_e32 v137, v51, v133
	v_sub_f32_e32 v136, v50, v132
	v_sub_f32_e32 v139, v53, v135
	v_sub_f32_e32 v138, v52, v134
	s_waitcnt vmcnt(1)
	v_lshlrev_b32_e32 v123, 16, v82
	v_and_b32_e32 v140, 0xffff0000, v82
	v_lshlrev_b32_e32 v141, 16, v83
	s_waitcnt vmcnt(0)
	v_lshlrev_b32_e32 v143, 16, v84
	v_and_b32_e32 v142, 0xffff0000, v83
	v_and_b32_e32 v146, 0xffff0000, v84
	v_lshlrev_b32_e32 v147, 16, v85
	v_and_b32_e32 v148, 0xffff0000, v85
	v_lshlrev_b32_e32 v20, 16, v62
	v_and_b32_e32 v21, 0xffff0000, v62
	v_lshlrev_b32_e32 v92, 16, v63
	v_and_b32_e32 v93, 0xffff0000, v63
	v_sub_f32_e32 v47, v47, v21
	v_sub_f32_e32 v46, v46, v20
	v_sub_f32_e32 v49, v49, v93
	v_sub_f32_e32 v48, v48, v92
	s_waitcnt vmcnt(0)
	v_pk_fma_f32 v[44:45], v[138:139], v[188:189], v[134:135]
	v_pk_fma_f32 v[42:43], v[136:137], v[186:187], v[132:133]
	s_waitcnt vmcnt(0)
	v_add_f32_e32 v38, v190, v123
	v_add_f32_e32 v39, v191, v140
	s_waitcnt vmcnt(0)
	v_pk_mul_f32 v[126:127], v[44:45], v[200:201]
	v_pk_mul_f32 v[124:125], v[42:43], v[198:199]
	v_mul_f32_e32 v123, 0xbfb8aa3b, v38
	v_mul_f32_e32 v134, 0xbfb8aa3b, v39
	v_pk_mul_f32 v[38:39], v[126:127], v[126:127]
	v_pk_mul_f32 v[132:133], v[124:125], v[124:125]
	v_exp_f32_e32 v123, v123
	v_exp_f32_e32 v136, v134
	v_pk_mov_b32 v[134:135], v[132:133], v[38:39] op_sel:[1,0]
	v_mov_b32_e32 v133, v39
	v_pk_add_f32 v[38:39], v[134:135], v[132:133]
	v_add_f32_e32 v40, v192, v141
	v_add_f32_e32 v38, v38, v39
	v_add_f32_e32 v39, 1.0, v123
	v_add_f32_e32 v123, 1.0, v136
	v_add_f32_dpp v38, v38, v38 quad_perm:[1,0,3,2] row_mask:0xf bank_mask:0xf bound_ctrl:1
	v_div_scale_f32 v132, s[16:17], v39, v39, 1.0
	s_nop 0
	v_add_f32_dpp v38, v38, v38 quad_perm:[2,3,0,1] row_mask:0xf bank_mask:0xf bound_ctrl:1
	v_div_scale_f32 v134, s[18:19], v123, v123, 1.0
	s_nop 0
	v_add_f32_dpp v38, v38, v38 row_half_mirror row_mask:0xf bank_mask:0xf bound_ctrl:1
	v_rcp_f32_e32 v136, v132
	v_rcp_f32_e32 v137, v134
	v_add_f32_dpp v38, v38, v38 row_mirror row_mask:0xf bank_mask:0xf bound_ctrl:1
	v_mul_f32_e32 v138, 0x4f800000, v38
	v_cmp_gt_f32_e32 vcc, s77, v38
	v_fma_f32 v139, -v132, v136, 1.0
	v_div_scale_f32 v133, s[16:17], 1.0, v39, 1.0
	v_cndmask_b32_e32 v38, v38, v138, vcc
	v_sqrt_f32_e32 v138, v38
	v_fma_f32 v140, -v134, v137, 1.0
	v_fmac_f32_e32 v136, v139, v136
	v_div_scale_f32 v135, s[18:19], 1.0, v123, 1.0
	v_fmac_f32_e32 v137, v140, v137
	v_mul_f32_e32 v139, v133, v136
	v_mul_f32_e32 v140, v135, v137
	v_fma_f32 v141, -v132, v139, v133
	v_add_u32_e32 v149, -1, v138
	v_add_f32_e32 v34, v194, v143
	v_fma_f32 v143, -v134, v140, v135
	v_add_u32_e32 v150, 1, v138
	v_fmac_f32_e32 v139, v141, v136
	v_fma_f32 v141, -v149, v138, v38
	v_fmac_f32_e32 v140, v143, v137
	v_fma_f32 v143, -v150, v138, v38
	v_cmp_ge_f32_e64 s[20:21], 0, v141
	v_fma_f32 v133, -v132, v139, v133
	v_fma_f32 v134, -v134, v140, v135
	v_cndmask_b32_e64 v132, v138, v149, s[20:21]
	v_cmp_lt_f32_e64 s[20:21], 0, v143
	v_mul_f32_e32 v40, 0xbfb8aa3b, v40
	v_exp_f32_e32 v40, v40
	v_cndmask_b32_e64 v132, v132, v150, s[20:21]
	v_mul_f32_e32 v138, 0x37800000, v132
	v_cndmask_b32_e32 v132, v132, v138, vcc
	v_cmp_class_f32_e32 vcc, v38, v118
	v_add_f32_e32 v40, 1.0, v40
	v_add_f32_e32 v41, v193, v142
	v_cndmask_b32_e32 v38, v132, v38, vcc
	v_max_f32_e32 v38, 0x2b8cbccc, v38
	v_div_scale_f32 v132, s[20:21], v38, v38, -1.0
	v_rcp_f32_e32 v138, v132
	v_div_scale_f32 v135, vcc, -1.0, v38, -1.0
	v_mul_f32_e32 v41, 0xbfb8aa3b, v41
	v_fma_f32 v141, -v132, v138, 1.0
	v_fmac_f32_e32 v138, v141, v138
	v_mul_f32_e32 v141, v135, v138
	v_fma_f32 v143, -v132, v141, v135
	v_fmac_f32_e32 v141, v143, v138
	v_fma_f32 v132, -v132, v141, v135
	v_div_fmas_f32 v132, v132, v138, v141
	s_mov_b64 vcc, s[16:17]
	v_div_fixup_f32 v132, v132, v38, -1.0
	v_div_fmas_f32 v38, v133, v136, v139
	s_mov_b64 vcc, s[18:19]
	v_div_fixup_f32 v38, v38, v39, 1.0
	v_div_fmas_f32 v39, v134, v137, v140
	v_div_fixup_f32 v39, v39, v123, 1.0
	v_div_scale_f32 v123, s[16:17], v40, v40, 1.0
	v_rcp_f32_e32 v133, v123
	v_exp_f32_e32 v41, v41
	v_add_f32_e32 v35, v195, v146
	v_mul_f32_e32 v34, 0xbfb8aa3b, v34
	v_fma_f32 v134, -v123, v133, 1.0
	v_fmac_f32_e32 v133, v134, v133
	v_div_scale_f32 v134, vcc, 1.0, v40, 1.0
	v_mul_f32_e32 v135, v134, v133
; __device__ __forceinline__ float sigmoidf_(float x) { return 1.0f / (1.0f + __expf(-x)); }
; __device__ __forceinline__ f32x4 cv_bf4(const u32x2 w) { return (f32x4){bflo(w.x), bfhi(w.x), bflo(w.y), bfhi(w.y)}; }
; __device__ __forceinline__ void scan_finish(const ScanPtrs& Q, int J, int ci, unsigned char* buf, int ltid, const LStage& L, int toff) {
;     ...
;         r = r + (rp - r) * *(const f32x4*)mu; k0 = k0 + (kp - k0) * *(const f32x4*)(mu + 512); v = v + (vp - v) * *(const f32x4*)(mu + 1024);
;         const f32x4 kk = k0 * *(const f32x4*)(Q.k_k + gc);
;         const float ss = allsum16((kk[0] * kk[0] + kk[1] * kk[1]) + (kk[2] * kk[2] + kk[3] * kk[3]));
;         const float inv = 1.0f / fmaxf(sqrtf(ss), 1e-12f);
;         const f32x4 kkn = kk * inv;
;         const f32x4 dw = cv_bf4(L.sw) + *(const f32x4*)(Q.decay0 + gc);
;         const f32x4 da = cv_bf4(L.sa) + *(const f32x4*)(Q.a0 + gc);
;         f32x4 dec, ain;
; #pragma unroll
;         for (int j = 0; j < 4; ++j) { dec[j] = __expf(-0.60653066f * sigmoidf_(dw[j])); ain[j] = sigmoidf_(da[j]); }
;         const f32x4 ka = *(const f32x4*)(Q.k_a + gc);
;         const f32x4 kf = k0 * (1.0f + (ain - 1.0f) * ka);
;         const f32x4 rkw = *(const f32x4*)(Q.r_k + gc);
;         const f32x4 pr = r * kf * rkw;
;         const float rk = allsum16((pr[0] + pr[1]) + (pr[2] + pr[3]));
;         unsigned char* tb = buf + tt * SC_TOKB + c * 4;
;         *(f32x4*)(tb) = -kkn; *(f32x4*)(tb + 256) = dec; *(f32x4*)(tb + 512) = kkn * ain; *(f32x4*)(tb + 768) = kf; *(f32x4*)(tb + 1024) = r;
;         if ((c >> 4) == jb.rs) *(f32x4*)(buf + tt * SC_TOKB + 1280 + (c & 15) * 4) = v;
;         if (jb.rs == 0 && c == 0) Q.rk[(size_t)tok * 8 + jb.h] = rk;
	v_fma_f32 v136, -v123, v135, v134
	v_fmac_f32_e32 v135, v136, v133
	v_fma_f32 v123, -v123, v135, v134
	v_div_fmas_f32 v123, v123, v133, v135
	v_add_f32_e32 v41, 1.0, v41
	v_div_fixup_f32 v40, v123, v40, 1.0
	v_div_scale_f32 v123, s[16:17], v41, v41, 1.0
	v_rcp_f32_e32 v133, v123
	v_mul_f32_e32 v35, 0xbfb8aa3b, v35
	v_exp_f32_e32 v34, v34
	v_exp_f32_e32 v35, v35
	v_fma_f32 v134, -v123, v133, 1.0
	v_fmac_f32_e32 v133, v134, v133
	v_div_scale_f32 v134, vcc, 1.0, v41, 1.0
	v_mul_f32_e32 v135, v134, v133
	v_fma_f32 v136, -v123, v135, v134
	v_fmac_f32_e32 v135, v136, v133
	v_fma_f32 v123, -v123, v135, v134
	v_div_fmas_f32 v123, v123, v133, v135
	v_pk_add_f32 v[34:35], v[34:35], 1.0 op_sel_hi:[1,0]
	v_div_fixup_f32 v41, v123, v41, 1.0
	v_div_scale_f32 v123, s[16:17], v35, v35, 1.0
	v_rcp_f32_e32 v133, v123
	v_add_f32_e32 v36, v196, v147
	v_add_f32_e32 v37, v197, v148
	v_mul_f32_e32 v36, 0xbfb8aa3b, v36
	v_fma_f32 v134, -v123, v133, 1.0
	v_fmac_f32_e32 v133, v134, v133
	v_div_scale_f32 v134, vcc, 1.0, v35, 1.0
	v_mul_f32_e32 v135, v134, v133
	v_fma_f32 v136, -v123, v135, v134
	v_fmac_f32_e32 v135, v136, v133
	v_fma_f32 v123, -v123, v135, v134
	v_div_scale_f32 v134, s[16:17], v34, v34, 1.0
	v_rcp_f32_e32 v136, v134
	v_mul_f32_e32 v37, 0xbfb8aa3b, v37
	v_exp_f32_e32 v36, v36
	v_exp_f32_e32 v37, v37
	v_div_fmas_f32 v123, v123, v133, v135
	v_div_fixup_f32 v135, v123, v35, 1.0
	v_fma_f32 v35, -v134, v136, 1.0
	v_fmac_f32_e32 v136, v35, v136
	v_div_scale_f32 v35, vcc, 1.0, v34, 1.0
	v_mul_f32_e32 v123, v35, v136
	v_pk_add_f32 v[36:37], v[36:37], 1.0 op_sel_hi:[1,0]
	v_fma_f32 v133, -v134, v123, v35
	v_fmac_f32_e32 v123, v133, v136
	v_div_scale_f32 v133, s[16:17], v37, v37, 1.0
	v_rcp_f32_e32 v137, v133
	v_fma_f32 v35, -v134, v123, v35
	v_div_fmas_f32 v35, v35, v136, v123
	v_div_fixup_f32 v134, v35, v34, 1.0
	v_fma_f32 v34, -v133, v137, 1.0
	v_fmac_f32_e32 v137, v34, v137
	v_div_scale_f32 v34, vcc, 1.0, v37, 1.0
	v_mul_f32_e32 v35, v34, v137
	v_fma_f32 v123, -v133, v35, v34
	v_fmac_f32_e32 v35, v123, v137
	v_div_scale_f32 v123, s[16:17], v36, v36, 1.0
	v_fma_f32 v34, -v133, v35, v34
	v_rcp_f32_e32 v133, v123
	v_div_fmas_f32 v34, v34, v137, v35
	v_div_fixup_f32 v37, v34, v37, 1.0
	v_mul_f32_e32 v38, 0xbf1b4598, v38
	v_fma_f32 v34, -v123, v133, 1.0
	v_fmac_f32_e32 v133, v34, v133
	v_div_scale_f32 v34, vcc, 1.0, v36, 1.0
	v_mul_f32_e32 v35, v34, v133
	v_fma_f32 v136, -v123, v35, v34
	v_fmac_f32_e32 v35, v136, v133
	v_fma_f32 v34, -v123, v35, v34
	v_div_fmas_f32 v34, v34, v133, v35
	v_div_fixup_f32 v36, v34, v36, 1.0
	s_waitcnt vmcnt(0)
	v_pk_fma_f32 v[34:35], v[48:49], v[204:205], v[92:93]
	v_pk_fma_f32 v[32:33], v[46:47], v[202:203], v[20:21]
	v_pk_add_f32 v[20:21], v[36:37], -1.0 op_sel_hi:[1,0]
	v_pk_add_f32 v[30:31], v[134:135], -1.0 op_sel_hi:[1,0]
	s_waitcnt vmcnt(0)
	v_pk_fma_f32 v[20:21], v[208:209], v[20:21], 1.0 op_sel_hi:[1,1,0]
	v_pk_fma_f32 v[30:31], v[206:207], v[30:31], 1.0 op_sel_hi:[1,1,0]
	v_pk_mul_f32 v[44:45], v[44:45], v[20:21]
	v_pk_mul_f32 v[42:43], v[42:43], v[30:31]
	v_pk_mul_f32 v[30:31], v[34:35], v[44:45]
	v_pk_mul_f32 v[20:21], v[32:33], v[42:43]
	s_waitcnt vmcnt(0)
	v_pk_mul_f32 v[30:31], v[212:213], v[30:31]
	v_pk_mul_f32 v[20:21], v[210:211], v[20:21]
	v_mul_f32_e32 v39, 0xbf1b4598, v39
	v_mul_f32_e32 v40, 0xbf1b4598, v40
	v_mul_f32_e32 v41, 0xbf1b4598, v41
	v_add_f32_e32 v20, v20, v21
	v_add_f32_e32 v21, v30, v31
	v_mul_f32_e32 v38, 0x3fb8aa3b, v38
	v_mul_f32_e32 v39, 0x3fb8aa3b, v39
	v_mul_f32_e32 v40, 0x3fb8aa3b, v40
	v_mul_f32_e32 v41, 0x3fb8aa3b, v41
	v_add_f32_e32 v20, v20, v21
	v_exp_f32_e32 v38, v38
	v_exp_f32_e32 v39, v39
	v_exp_f32_e32 v40, v40
	v_exp_f32_e32 v41, v41
	v_add_f32_dpp v20, v20, v20 quad_perm:[1,0,3,2] row_mask:0xf bank_mask:0xf bound_ctrl:1
	v_add_u32_e32 v30, s6, v99
	v_mov_b32_e32 v21, 0
	v_add_f32_dpp v20, v20, v20 quad_perm:[2,3,0,1] row_mask:0xf bank_mask:0xf bound_ctrl:1
	v_add_u32_e32 v31, v30, v100
	v_pk_mul_f32 v[48:49], v[126:127], v[132:133] op_sel_hi:[1,0]
	v_add_f32_dpp v20, v20, v20 row_half_mirror row_mask:0xf bank_mask:0xf bound_ctrl:1
	v_pk_mul_f32 v[46:47], v[124:125], v[132:133] op_sel_hi:[1,0]
	ds_write_b128 v31, v[46:49]
	ds_write_b128 v31, v[38:41] offset:256
	v_mov_b32_dpp v21, v20 row_mirror row_mask:0xf bank_mask:0xf
	v_pk_mul_f32 v[38:39], v[48:49], v[36:37] neg_lo:[1,0] neg_hi:[1,0]
	v_pk_mul_f32 v[36:37], v[46:47], v[134:135] neg_lo:[1,0] neg_hi:[1,0]
	v_cmp_eq_u32_e32 vcc, v101, v121
	ds_write_b128 v31, v[36:39] offset:512
	ds_write_b128 v31, v[42:45] offset:768
	ds_write_b128 v31, v[32:35] offset:1024
	s_and_saveexec_b64 s[16:17], vcc
	s_cbranch_execz .LBB0_1631
	v_lshl_add_u64 v[32:33], s[58:59], 0, v[18:19]
	v_add_co_u32_e32 v32, vcc, 0x1000, v32
	v_lshlrev_b32_e32 v36, 16, v72
	s_nop 0
	v_addc_co_u32_e32 v33, vcc, 0, v33, vcc
	v_and_b32_e32 v37, 0xffff0000, v72
	v_lshlrev_b32_e32 v38, 16, v73
	v_and_b32_e32 v39, 0xffff0000, v73
	v_sub_f32_e32 v29, v29, v39
	v_sub_f32_e32 v28, v28, v38
	v_sub_f32_e32 v27, v27, v37
	v_sub_f32_e32 v26, v26, v36
	v_add_u32_e32 v18, v30, v102
	s_waitcnt vmcnt(0)
	v_pk_fma_f32 v[26:27], v[26:27], v[214:215], v[36:37]
	v_pk_fma_f32 v[28:29], v[28:29], v[216:217], v[38:39]
	ds_write_b128 v18, v[26:29] offset:1280

; __device__ __forceinline__ float sigmoidf_(float x) { return 1.0f / (1.0f + __expf(-x)); }
; __device__ __forceinline__ f32x4 cv_bf4(const u32x2 w) { return (f32x4){bflo(w.x), bfhi(w.x), bflo(w.y), bfhi(w.y)}; }
; __device__ __forceinline__ void scan_finish(const ScanPtrs& Q, int J, int ci, unsigned char* buf, int ltid, const LStage& L, int toff) {
;     ...
;         const float* mu = Q.mu + gc;
;         r = r + (rp - r) * *(const f32x4*)mu; k0 = k0 + (kp - k0) * *(const f32x4*)(mu + 512); v = v + (vp - v) * *(const f32x4*)(mu + 1024);
;         const f32x4 kk = k0 * *(const f32x4*)(Q.k_k + gc);
;         const float ss = allsum16((kk[0] * kk[0] + kk[1] * kk[1]) + (kk[2] * kk[2] + kk[3] * kk[3]));
;         const float inv = 1.0f / fmaxf(sqrtf(ss), 1e-12f);
;         const f32x4 kkn = kk * inv;
;         const f32x4 dw = cv_bf4(L.sw) + *(const f32x4*)(Q.decay0 + gc);
;         const f32x4 da = cv_bf4(L.sa) + *(const f32x4*)(Q.a0 + gc);
;         f32x4 dec, ain;
; #pragma unroll
;         for (int j = 0; j < 4; ++j) { dec[j] = __expf(-0.60653066f * sigmoidf_(dw[j])); ain[j] = sigmoidf_(da[j]); }
;         const f32x4 ka = *(const f32x4*)(Q.k_a + gc);
;         const f32x4 kf = k0 * (1.0f + (ain - 1.0f) * ka);
;         const f32x4 rkw = *(const f32x4*)(Q.r_k + gc);
;         const f32x4 pr = r * kf * rkw;
;         const float rk = allsum16((pr[0] + pr[1]) + (pr[2] + pr[3]));
;         unsigned char* tb = buf + tt * SC_TOKB + c * 4;
;         *(f32x4*)(tb) = -kkn; *(f32x4*)(tb + 256) = dec; *(f32x4*)(tb + 512) = kkn * ain; *(f32x4*)(tb + 768) = kf; *(f32x4*)(tb + 1024) = r;
.LBB0_1636:
	s_or_b64 exec, exec, s[14:15]
	v_lshl_or_b32 v18, v91, 8, v100
	s_waitcnt vmcnt(1)
	v_lshlrev_b32_e32 v134, 16, v60
	v_and_b32_e32 v135, 0xffff0000, v60
	v_lshlrev_b32_e32 v136, 16, v61
	v_and_b32_e32 v137, 0xffff0000, v61
	v_sub_f32_e32 v139, v92, v135
	v_sub_f32_e32 v138, v52, v134
	v_sub_f32_e32 v93, v93, v137
	v_sub_f32_e32 v92, v53, v136
	s_waitcnt vmcnt(1)
	v_lshlrev_b32_e32 v140, 16, v78
	v_and_b32_e32 v141, 0xffff0000, v78
	v_lshlrev_b32_e32 v142, 16, v79
	s_waitcnt vmcnt(1)
	v_lshlrev_b32_e32 v146, 16, v80
	v_and_b32_e32 v143, 0xffff0000, v79
	v_and_b32_e32 v147, 0xffff0000, v80
	v_lshlrev_b32_e32 v148, 16, v81
	v_and_b32_e32 v149, 0xffff0000, v81
	v_lshlrev_b32_e32 v20, 16, v56
	v_and_b32_e32 v21, 0xffff0000, v56
	v_lshlrev_b32_e32 v42, 16, v57
	v_and_b32_e32 v43, 0xffff0000, v57
	v_sub_f32_e32 v45, v45, v21
	v_sub_f32_e32 v44, v44, v20
	v_sub_f32_e32 v47, v47, v43
	v_sub_f32_e32 v46, v46, v42
	s_waitcnt vmcnt(1)
	v_pk_fma_f32 v[40:41], v[92:93], v[188:189], v[136:137]
	v_pk_fma_f32 v[38:39], v[138:139], v[186:187], v[134:135]
	s_waitcnt vmcnt(1)
	v_add_f32_e32 v34, v190, v140
	v_add_f32_e32 v35, v191, v141
	s_waitcnt vmcnt(1)
	v_pk_mul_f32 v[52:53], v[40:41], v[200:201]
	v_pk_mul_f32 v[92:93], v[38:39], v[198:199]
	v_mul_f32_e32 v124, 0xbfb8aa3b, v34
	v_mul_f32_e32 v125, 0xbfb8aa3b, v35
	v_pk_mul_f32 v[34:35], v[52:53], v[52:53]
	v_pk_mul_f32 v[122:123], v[92:93], v[92:93]
	v_exp_f32_e32 v134, v124
	v_exp_f32_e32 v135, v125
	v_pk_mov_b32 v[124:125], v[122:123], v[34:35] op_sel:[1,0]
	v_mov_b32_e32 v123, v35
	v_pk_add_f32 v[34:35], v[124:125], v[122:123]
	v_add_f32_e32 v123, 1.0, v135
	v_add_f32_e32 v34, v34, v35
	v_add_f32_e32 v35, 1.0, v134
	v_div_scale_f32 v122, s[14:15], v35, v35, 1.0
	v_add_f32_dpp v34, v34, v34 quad_perm:[1,0,3,2] row_mask:0xf bank_mask:0xf bound_ctrl:1
	v_div_scale_f32 v125, s[16:17], v123, v123, 1.0
	s_nop 0
	v_add_f32_dpp v34, v34, v34 quad_perm:[2,3,0,1] row_mask:0xf bank_mask:0xf bound_ctrl:1
	v_rcp_f32_e32 v135, v122
	v_rcp_f32_e32 v136, v125
	v_add_f32_dpp v34, v34, v34 row_half_mirror row_mask:0xf bank_mask:0xf bound_ctrl:1
	v_div_scale_f32 v124, s[14:15], 1.0, v35, 1.0
	s_nop 0
	v_add_f32_dpp v34, v34, v34 row_mirror row_mask:0xf bank_mask:0xf bound_ctrl:1
	v_mul_f32_e32 v137, 0x4f800000, v34
	v_cmp_gt_f32_e32 vcc, s77, v34
	v_fma_f32 v138, -v122, v135, 1.0
	v_fma_f32 v139, -v125, v136, 1.0
	v_cndmask_b32_e32 v34, v34, v137, vcc
	v_sqrt_f32_e32 v137, v34
	v_fmac_f32_e32 v135, v138, v135
	v_div_scale_f32 v134, s[16:17], 1.0, v123, 1.0
	v_fmac_f32_e32 v136, v139, v136
	v_mul_f32_e32 v138, v124, v135
	v_add_f32_e32 v36, v192, v142
	v_mul_f32_e32 v139, v134, v136
	v_fma_f32 v140, -v122, v138, v124
	v_add_u32_e32 v142, -1, v137
	v_add_f32_e32 v30, v194, v146
	v_fma_f32 v141, -v125, v139, v134
	v_add_u32_e32 v146, 1, v137
	v_fmac_f32_e32 v138, v140, v135
	v_fma_f32 v140, -v142, v137, v34
	v_fmac_f32_e32 v139, v141, v136
	v_fma_f32 v141, -v146, v137, v34
	v_cmp_ge_f32_e64 s[18:19], 0, v140
	v_fma_f32 v124, -v122, v138, v124
	v_fma_f32 v125, -v125, v139, v134
	v_cndmask_b32_e64 v122, v137, v142, s[18:19]
	v_cmp_lt_f32_e64 s[18:19], 0, v141
	v_mul_f32_e32 v36, 0xbfb8aa3b, v36
	v_exp_f32_e32 v36, v36
	v_cndmask_b32_e64 v122, v122, v146, s[18:19]
	v_mul_f32_e32 v137, 0x37800000, v122
	v_cndmask_b32_e32 v122, v122, v137, vcc
	v_cmp_class_f32_e32 vcc, v34, v118
	v_add_f32_e32 v36, 1.0, v36
	v_add_f32_e32 v37, v193, v143
	v_cndmask_b32_e32 v34, v122, v34, vcc
	v_max_f32_e32 v34, 0x2b8cbccc, v34
	v_div_scale_f32 v122, s[18:19], v34, v34, -1.0
	v_rcp_f32_e32 v137, v122
	v_div_scale_f32 v134, vcc, -1.0, v34, -1.0
	v_mul_f32_e32 v37, 0xbfb8aa3b, v37
	v_fma_f32 v140, -v122, v137, 1.0
	v_fmac_f32_e32 v137, v140, v137
	v_mul_f32_e32 v140, v134, v137
	v_fma_f32 v141, -v122, v140, v134
	v_fmac_f32_e32 v140, v141, v137
	v_fma_f32 v122, -v122, v140, v134
	v_div_fmas_f32 v122, v122, v137, v140
	s_mov_b64 vcc, s[14:15]
	v_div_fixup_f32 v122, v122, v34, -1.0
	v_div_fmas_f32 v34, v124, v135, v138
	s_mov_b64 vcc, s[16:17]
	v_div_fixup_f32 v34, v34, v35, 1.0
	v_div_fmas_f32 v35, v125, v136, v139
	v_div_fixup_f32 v35, v35, v123, 1.0
	v_div_scale_f32 v123, s[14:15], v36, v36, 1.0
	v_rcp_f32_e32 v124, v123
	v_exp_f32_e32 v37, v37
	v_add_f32_e32 v31, v195, v147
	v_mul_f32_e32 v30, 0xbfb8aa3b, v30
	v_fma_f32 v125, -v123, v124, 1.0
	v_fmac_f32_e32 v124, v125, v124
	v_div_scale_f32 v125, vcc, 1.0, v36, 1.0
	v_mul_f32_e32 v134, v125, v124
	v_fma_f32 v135, -v123, v134, v125
	v_fmac_f32_e32 v134, v135, v124
	v_fma_f32 v123, -v123, v134, v125
	v_div_fmas_f32 v123, v123, v124, v134
	v_add_f32_e32 v37, 1.0, v37
	v_div_fixup_f32 v36, v123, v36, 1.0
	v_div_scale_f32 v123, s[14:15], v37, v37, 1.0
	v_rcp_f32_e32 v124, v123
	v_mul_f32_e32 v31, 0xbfb8aa3b, v31
	v_exp_f32_e32 v30, v30
	v_exp_f32_e32 v31, v31
	v_fma_f32 v125, -v123, v124, 1.0
	v_fmac_f32_e32 v124, v125, v124
	v_div_scale_f32 v125, vcc, 1.0, v37, 1.0
	v_mul_f32_e32 v134, v125, v124
	v_fma_f32 v135, -v123, v134, v125
	v_fmac_f32_e32 v134, v135, v124
	v_fma_f32 v123, -v123, v134, v125
	v_div_fmas_f32 v123, v123, v124, v134
	v_pk_add_f32 v[30:31], v[30:31], 1.0 op_sel_hi:[1,0]
	v_div_fixup_f32 v37, v123, v37, 1.0
	v_div_scale_f32 v123, s[14:15], v31, v31, 1.0
	v_rcp_f32_e32 v124, v123
	v_add_f32_e32 v32, v196, v148
	v_add_f32_e32 v33, v197, v149
	v_mul_f32_e32 v32, 0xbfb8aa3b, v32
	v_fma_f32 v125, -v123, v124, 1.0
	v_fmac_f32_e32 v124, v125, v124
	v_div_scale_f32 v125, vcc, 1.0, v31, 1.0
	v_mul_f32_e32 v134, v125, v124
	v_fma_f32 v135, -v123, v134, v125
	v_fmac_f32_e32 v134, v135, v124
	v_div_scale_f32 v135, s[14:15], v30, v30, 1.0
	v_rcp_f32_e32 v136, v135
	v_mul_f32_e32 v33, 0xbfb8aa3b, v33
	v_fma_f32 v123, -v123, v134, v125
	v_exp_f32_e32 v32, v32
	v_exp_f32_e32 v33, v33
	v_div_fmas_f32 v123, v123, v124, v134
	v_div_fixup_f32 v125, v123, v31, 1.0
	v_fma_f32 v31, -v135, v136, 1.0
	v_fmac_f32_e32 v136, v31, v136
	v_div_scale_f32 v31, vcc, 1.0, v30, 1.0
	v_mul_f32_e32 v123, v31, v136
	v_pk_add_f32 v[32:33], v[32:33], 1.0 op_sel_hi:[1,0]
	v_fma_f32 v124, -v135, v123, v31
	v_fmac_f32_e32 v123, v124, v136
	v_div_scale_f32 v134, s[14:15], v33, v33, 1.0
	v_fma_f32 v31, -v135, v123, v31
	v_rcp_f32_e32 v135, v134
	v_div_fmas_f32 v31, v31, v136, v123
	v_div_fixup_f32 v124, v31, v30, 1.0
	v_mul_f32_e32 v34, 0xbf1b4598, v34
	v_fma_f32 v30, -v134, v135, 1.0
	v_fmac_f32_e32 v135, v30, v135
	v_div_scale_f32 v30, vcc, 1.0, v33, 1.0
	v_mul_f32_e32 v31, v30, v135
	v_fma_f32 v123, -v134, v31, v30
	v_fmac_f32_e32 v31, v123, v135
	v_div_scale_f32 v123, s[14:15], v32, v32, 1.0
	v_fma_f32 v30, -v134, v31, v30
	v_rcp_f32_e32 v134, v123
	v_div_fmas_f32 v30, v30, v135, v31
	v_div_fixup_f32 v33, v30, v33, 1.0
	v_mul_f32_e32 v35, 0xbf1b4598, v35
	v_fma_f32 v30, -v123, v134, 1.0
	v_fmac_f32_e32 v134, v30, v134
	v_div_scale_f32 v30, vcc, 1.0, v32, 1.0
	v_mul_f32_e32 v31, v30, v134
	v_fma_f32 v135, -v123, v31, v30
	v_fmac_f32_e32 v31, v135, v134
	v_fma_f32 v30, -v123, v31, v30
	v_div_fmas_f32 v30, v30, v134, v31
	v_div_fixup_f32 v32, v30, v32, 1.0
	s_waitcnt vmcnt(1)
; __device__ __forceinline__ void scan_finish(const ScanPtrs& Q, int J, int ci, unsigned char* buf, int ltid, const LStage& L, int toff) {
;     ...
;         const f32x4 kf = k0 * (1.0f + (ain - 1.0f) * ka);
;         const f32x4 rkw = *(const f32x4*)(Q.r_k + gc);
;         const f32x4 pr = r * kf * rkw;
;         const float rk = allsum16((pr[0] + pr[1]) + (pr[2] + pr[3]));
;         unsigned char* tb = buf + tt * SC_TOKB + c * 4;
;         *(f32x4*)(tb) = -kkn; *(f32x4*)(tb + 256) = dec; *(f32x4*)(tb + 512) = kkn * ain; *(f32x4*)(tb + 768) = kf; *(f32x4*)(tb + 1024) = r;
;         if ((c >> 4) == jb.rs) *(f32x4*)(buf + tt * SC_TOKB + 1280 + (c & 15) * 4) = v;
	v_pk_fma_f32 v[30:31], v[46:47], v[204:205], v[42:43]
	v_pk_fma_f32 v[28:29], v[44:45], v[202:203], v[20:21]
	v_pk_add_f32 v[20:21], v[32:33], -1.0 op_sel_hi:[1,0]
	v_pk_add_f32 v[26:27], v[124:125], -1.0 op_sel_hi:[1,0]
	s_waitcnt vmcnt(1)
	v_pk_fma_f32 v[20:21], v[208:209], v[20:21], 1.0 op_sel_hi:[1,1,0]
	v_pk_fma_f32 v[26:27], v[206:207], v[26:27], 1.0 op_sel_hi:[1,1,0]
	v_pk_mul_f32 v[40:41], v[40:41], v[20:21]
	v_pk_mul_f32 v[38:39], v[38:39], v[26:27]
	v_pk_mul_f32 v[26:27], v[30:31], v[40:41]
	v_pk_mul_f32 v[20:21], v[28:29], v[38:39]
	s_waitcnt vmcnt(1)
	v_pk_mul_f32 v[26:27], v[212:213], v[26:27]
	v_pk_mul_f32 v[20:21], v[210:211], v[20:21]
	v_mul_f32_e32 v36, 0xbf1b4598, v36
	v_mul_f32_e32 v37, 0xbf1b4598, v37
	v_add_f32_e32 v20, v20, v21
	v_add_f32_e32 v21, v26, v27
	v_mul_f32_e32 v34, 0x3fb8aa3b, v34
	v_mul_f32_e32 v35, 0x3fb8aa3b, v35
	v_mul_f32_e32 v36, 0x3fb8aa3b, v36
	v_mul_f32_e32 v37, 0x3fb8aa3b, v37
	v_add_f32_e32 v20, v20, v21
	v_exp_f32_e32 v34, v34
	v_exp_f32_e32 v35, v35
	v_exp_f32_e32 v36, v36
	v_exp_f32_e32 v37, v37
	v_add_f32_dpp v20, v20, v20 quad_perm:[1,0,3,2] row_mask:0xf bank_mask:0xf bound_ctrl:1
	v_add_u32_e32 v26, s6, v105
	v_mov_b32_e32 v21, 0
	v_add_f32_dpp v20, v20, v20 quad_perm:[2,3,0,1] row_mask:0xf bank_mask:0xf bound_ctrl:1
	v_add_u32_e32 v27, v26, v100
	v_pk_mul_f32 v[44:45], v[52:53], v[122:123] op_sel_hi:[1,0]
	v_add_f32_dpp v20, v20, v20 row_half_mirror row_mask:0xf bank_mask:0xf bound_ctrl:1
	v_pk_mul_f32 v[42:43], v[92:93], v[122:123] op_sel_hi:[1,0]
	ds_write_b128 v27, v[42:45]
	ds_write_b128 v27, v[34:37] offset:256
	v_mov_b32_dpp v21, v20 row_mirror row_mask:0xf bank_mask:0xf
	v_pk_mul_f32 v[34:35], v[44:45], v[32:33] neg_lo:[1,0] neg_hi:[1,0]
	v_pk_mul_f32 v[32:33], v[42:43], v[124:125] neg_lo:[1,0] neg_hi:[1,0]
	v_cmp_eq_u32_e32 vcc, v101, v121
	ds_write_b128 v27, v[32:35] offset:512
	ds_write_b128 v27, v[38:41] offset:768
	ds_write_b128 v27, v[28:31] offset:1024
	s_and_saveexec_b64 s[14:15], vcc
	s_cbranch_execz .LBB0_1638
	v_lshl_add_u64 v[28:29], s[58:59], 0, v[18:19]
	v_add_co_u32_e32 v28, vcc, 0x1000, v28
	v_lshlrev_b32_e32 v32, 16, v68
	s_nop 0
	v_addc_co_u32_e32 v29, vcc, 0, v29, vcc
	v_and_b32_e32 v33, 0xffff0000, v68
	v_lshlrev_b32_e32 v34, 16, v69
	v_and_b32_e32 v35, 0xffff0000, v69
	v_add_u32_e32 v18, v26, v102
	v_sub_f32_e32 v37, v51, v35
	v_sub_f32_e32 v36, v50, v34
	v_sub_f32_e32 v27, v49, v33
	v_sub_f32_e32 v26, v48, v32
	s_waitcnt vmcnt(1)
	v_pk_fma_f32 v[26:27], v[26:27], v[214:215], v[32:33]
	v_pk_fma_f32 v[28:29], v[36:37], v[216:217], v[34:35]
	ds_write_b128 v18, v[26:29] offset:1280

; __global__ __launch_bounds__(512, 2) void mega_kernel(Params P) {
	.amdhsa_kernel _Z11mega_kernel6Params
		.amdhsa_group_segment_fixed_size 0
		.amdhsa_private_segment_fixed_size 0
		.amdhsa_kernarg_size 616
		.amdhsa_user_sgpr_count 2
		.amdhsa_user_sgpr_dispatch_ptr 0
		.amdhsa_user_sgpr_queue_ptr 0
		.amdhsa_user_sgpr_kernarg_segment_ptr 1
		.amdhsa_user_sgpr_dispatch_id 0
		.amdhsa_user_sgpr_kernarg_preload_length 0
		.amdhsa_user_sgpr_kernarg_preload_offset 0
		.amdhsa_user_sgpr_private_segment_size 0
		.amdhsa_uses_dynamic_stack 0
		.amdhsa_enable_private_segment 0
		.amdhsa_system_sgpr_workgroup_id_x 1
		.amdhsa_system_sgpr_workgroup_id_y 0
		.amdhsa_system_sgpr_workgroup_id_z 0
		.amdhsa_system_sgpr_workgroup_info 0
		.amdhsa_system_vgpr_workitem_id 2
		.amdhsa_next_free_vgpr 256
		.amdhsa_next_free_sgpr 102
		.amdhsa_accum_offset 256
		.amdhsa_reserve_vcc 1
		.amdhsa_float_round_mode_32 0
		.amdhsa_float_round_mode_16_64 0
		.amdhsa_float_denorm_mode_32 3
		.amdhsa_float_denorm_mode_16_64 3
		.amdhsa_dx10_clamp 1
		.amdhsa_ieee_mode 1
		.amdhsa_fp16_overflow 0
		.amdhsa_tg_split 0
		.amdhsa_exception_fp_ieee_invalid_op 0
		.amdhsa_exception_fp_denorm_src 0
		.amdhsa_exception_fp_ieee_div_zero 0
		.amdhsa_exception_fp_ieee_overflow 0
		.amdhsa_exception_fp_ieee_underflow 0
		.amdhsa_exception_fp_ieee_inexact 0
		.amdhsa_exception_int_div_zero 0
	.end_amdhsa_kernel

; __global__ __launch_bounds__(512, 2) void mega_kernel(Params P) {
amdhsa.kernels:
  - .agpr_count:     0
    .args:
      - .offset:         0
        .size:           360
        .value_kind:     by_value
      - .offset:         360
        .size:           4
        .value_kind:     hidden_block_count_x
      - .offset:         364
        .size:           4
        .value_kind:     hidden_block_count_y
      - .offset:         368
        .size:           4
        .value_kind:     hidden_block_count_z
      - .offset:         372
        .size:           2
        .value_kind:     hidden_group_size_x
      - .offset:         374
        .size:           2
        .value_kind:     hidden_group_size_y
      - .offset:         376
        .size:           2
        .value_kind:     hidden_group_size_z
      - .offset:         378
        .size:           2
        .value_kind:     hidden_remainder_x
      - .offset:         380
        .size:           2
        .value_kind:     hidden_remainder_y
      - .offset:         382
        .size:           2
        .value_kind:     hidden_remainder_z
      - .offset:         400
        .size:           8
        .value_kind:     hidden_global_offset_x
      - .offset:         408
        .size:           8
        .value_kind:     hidden_global_offset_y
      - .offset:         416
        .size:           8
        .value_kind:     hidden_global_offset_z
      - .offset:         424
        .size:           2
        .value_kind:     hidden_grid_dims
      - .offset:         448
        .size:           8
        .value_kind:     hidden_multigrid_sync_arg
      - .offset:         480
        .size:           4
        .value_kind:     hidden_dynamic_lds_size
    .group_segment_fixed_size: 0
    .kernarg_segment_align: 8
    .kernarg_segment_size: 616
    .language:       OpenCL C
    .language_version:
      - 2
      - 0
    .max_flat_workgroup_size: 512
    .name:           _Z11mega_kernel6Params
    .private_segment_fixed_size: 0
    .sgpr_count:     108
    .sgpr_spill_count: 10
    .symbol:         _Z11mega_kernel6Params.kd
    .uniform_work_group_size: 1
    .uses_dynamic_stack: false
    .vgpr_count:     256
    .vgpr_spill_count: 0
    .wavefront_size: 64
